# norm phase 1: row loads de-serialized (one counted wait instead of three full waits per iteration)
# baseline (speedup 1.0000x reference)
; __device__ __forceinline__ u16 f2bf(float x) { unsigned u = __float_as_uint(x); u += 0x7fffu + ((u >> 16) & 1u); return (u16)(u >> 16); }
; __device__ __forceinline__ size_t a_off(int row, int col, int nks) { return ((size_t)((row >> 8) * nks + (col >> 5)) << 13) + ((row & 255) << 5) + swzc(row, col & 31); }
; template <int MODE>
; __device__ __forceinline__ void norm_phase(const Params& p, const float* src, const float* w, const float* modl, int sh_off, int sc_off,
;                            char* smem, int bid, int nblk) {
;     ...
;     for (int i = 0; i < 4; ++i) ss += v[i][0] * v[i][0] + v[i][1] * v[i][1] + v[i][2] * v[i][2] + v[i][3] * v[i][3];
; #pragma unroll
;     for (int o = 32; o >= 1; o >>= 1) ss += __shfl_xor(ss, o);
;     const float rstd = rsqrtf(ss * (1.f / 1024.f) + 1e-6f);
;     const int b = row >> 13;
;     float dots[8];
;     if (MODE == 1) { for (int j = 0; j < 8; ++j) dots[j] = 0.f; }
; #pragma unroll
;     for (int i = 0; i < 4; ++i) {
;       const int c0 = i * 256 + lane * 4;
;       f32x4 ww = *(const f32x4*)(w + c0);
;       f32x4 y;
;       if (MODE == 2) {
; #pragma unroll
;         for (int e = 0; e < 4; ++e) y[e] = v[i][e] * rstd * ww[e];
;         *(f32x4*)(p.out + (size_t)row * 1024 + c0) = y;
;       } else {
;         f32x4 sc = *(const f32x4*)(modl + (size_t)b * 6144 + sc_off + c0);
;         f32x4 sh = *(const f32x4*)(modl + (size_t)b * 6144 + sh_off + c0);
; #pragma unroll
;         for (int e = 0; e < 4; ++e) y[e] = v[i][e] * rstd * ww[e] * (1.f + sc[e]) + sh[e];
;         uint2 pk; pk.x = (unsigned)f2bf(y[0]) | ((unsigned)f2bf(y[1]) << 16); pk.y = (unsigned)f2bf(y[2]) | ((unsigned)f2bf(y[3]) << 16);
;         *(uint2*)(hn + a_off(row, c0, 32)) = pk;
;         if (MODE == 1) {
; #pragma unroll
;           for (int e = 0; e < 4; ++e) {
;             f32x4 w0 = *(const f32x4*)(wba + (c0 + e) * 8), w1 = *(const f32x4*)(wba + (c0 + e) * 8 + 4);
; #pragma unroll
;             for (int j = 0; j < 4; ++j) { dots[j] += y[e] * w0[j]; dots[4 + j] += y[e] * w1[j]; }
;     ...
;     for (int i = 0; i < 4; ++i) v0[i] = *(const f32x4*)(src + (size_t)row * 1024 + i * 256 + lane * 4);
; #pragma unroll
;     for (int i = 0; i < 4; ++i) v1[i] = has1 ? *(const f32x4*)(src + (size_t)row1 * 1024 + i * 256 + lane * 4) : f32x4{0.f, 0.f, 0.f, 0.f};
.LBB0_103:
	s_or_b64 exec, exec, s[0:1]
	v_mov_b32_e32 v180, 0
	v_mov_b32_e32 v130, 0
	v_mov_b32_e32 v178, 0
	s_and_saveexec_b64 s[0:1], s[4:5]
	s_cbranch_execz .LBB0_105
	global_load_dwordx4 v[232:235], v[182:183], off offset:2048
.LBB0_105:
	s_or_b64 exec, exec, s[0:1]
	v_mov_b32_e32 v129, 0
	v_mov_b32_e32 v181, 0
	v_mov_b32_e32 v131, 0
	v_mov_b32_e32 v179, 0
	s_and_saveexec_b64 s[0:1], s[4:5]
	s_cbranch_execz .LBB0_107
	global_load_dwordx4 v[236:239], v[182:183], off offset:3072
.LBB0_107:
	s_or_b64 exec, exec, s[0:1]
	v_ashrrev_i32_e32 v160, 13, v156
	v_mul_i32_i24_e32 v182, 0x1800, v160
	v_readlane_b32 s0, v244, 23
	v_ashrrev_i32_e32 v183, 31, v182
	v_readlane_b32 s1, v244, 24
	v_lshlrev_b32_e32 v160, 2, v158
	global_load_dwordx4 v[210:213], v[164:165], off
	v_lshl_add_u64 v[182:183], v[182:183], 2, s[0:1]
	v_lshl_add_u64 v[184:185], v[182:183], 0, s[30:31]
	v_lshl_add_u64 v[214:215], v[184:185], 0, v[160:161]
	global_load_dwordx4 v[214:217], v[214:215], off
	v_lshl_add_u64 v[182:183], v[182:183], 0, v[160:161]
	global_load_dwordx4 v[218:221], v[182:183], off
	s_waitcnt vmcnt(3)
	s_and_saveexec_b64 s[98:99], s[4:5]
	v_mov_b32_e32 v128, v232
	v_mov_b32_e32 v180, v233
	v_mov_b32_e32 v130, v234
	v_mov_b32_e32 v178, v235
	v_mov_b32_e32 v129, v236
	v_mov_b32_e32 v181, v237
	v_mov_b32_e32 v131, v238
	v_mov_b32_e32 v179, v239
	s_or_b64 exec, exec, s[98:99]
	s_waitcnt vmcnt(6)
	v_pk_mul_f32 v[222:223], v[152:153], v[152:153]
	s_waitcnt vmcnt(5)
	v_pk_mul_f32 v[224:225], v[148:149], v[148:149]
	v_pk_mul_f32 v[186:187], v[154:155], v[154:155]
	v_pk_mul_f32 v[188:189], v[150:151], v[150:151]
	v_mov_b32_e32 v226, v222
	v_mov_b32_e32 v227, v224
	v_mov_b32_e32 v224, v223
	v_pk_add_f32 v[222:223], v[226:227], v[224:225]
	v_mov_b32_e32 v224, v186
	v_mov_b32_e32 v225, v188
	v_pk_add_f32 v[222:223], v[224:225], v[222:223]
	v_mov_b32_e32 v188, v187
	v_pk_add_f32 v[186:187], v[188:189], v[222:223]
	s_waitcnt vmcnt(3)
	v_mov_b32_e32 v222, v141
	v_mov_b32_e32 v223, v145
	v_mov_b32_e32 v188, v140
	v_mov_b32_e32 v189, v144
	v_pk_mul_f32 v[222:223], v[222:223], v[222:223]
	v_add_f32_e32 v171, v186, v187
	v_pk_fma_f32 v[188:189], v[188:189], v[188:189], v[222:223]
	v_mov_b32_e32 v222, v142
	v_mov_b32_e32 v223, v146
	v_pk_fma_f32 v[188:189], v[222:223], v[222:223], v[188:189]
	v_mov_b32_e32 v222, v143
	v_mov_b32_e32 v223, v147
	v_pk_fma_f32 v[188:189], v[222:223], v[222:223], v[188:189]
	v_mov_b32_e32 v223, v154
	v_add_f32_e32 v171, v189, v171
	v_add_f32_e32 v171, v188, v171
	ds_bpermute_b32 v173, v159, v171
	v_mov_b32_e32 v154, v153
	v_ashrrev_i32_e32 v175, 3, v156
	v_and_b32_e32 v209, 0xffffffe0, v175
	v_and_b32_e32 v188, 24, v202
	s_waitcnt lgkmcnt(0)
	v_add_f32_e32 v171, v171, v173
	ds_bpermute_b32 v173, v191, v171
	v_mov_b32_e32 v222, v152
	v_or_b32_e32 v152, v209, v196
	v_and_b32_e32 v186, 0x1fe0, v203
	v_mov_b32_e32 v187, v161
	s_waitcnt lgkmcnt(0)
	v_add_f32_e32 v171, v171, v173
	ds_bpermute_b32 v173, v192, v171
	v_lshlrev_b32_e32 v186, 1, v186
	v_mov_b32_e32 v189, v161
	s_waitcnt lgkmcnt(0)
	v_add_f32_e32 v171, v171, v173
	ds_bpermute_b32 v173, v193, v171
	s_waitcnt lgkmcnt(0)
	v_add_f32_e32 v153, v171, v173
	ds_bpermute_b32 v171, v194, v153
	v_sub_u32_e32 v173, 0, v188
	v_xor_b32_e32 v173, v158, v173
	v_and_or_b32 v173, v173, 24, v197
	v_lshlrev_b32_e32 v188, 1, v173
	s_waitcnt lgkmcnt(0)
	v_add_f32_e32 v171, v153, v171
	ds_bpermute_b32 v175, v195, v171
	v_ashrrev_i32_e32 v153, 31, v152
	v_lshlrev_b64 v[152:153], 14, v[152:153]
	v_lshl_add_u64 v[152:153], s[62:63], 0, v[152:153]
	v_lshl_add_u64 v[152:153], v[152:153], 0, v[186:187]
	s_waitcnt lgkmcnt(0)
	v_add_f32_e32 v171, v171, v175
	v_fmamk_f32 v171, v171, 0x3a800000, v157
	v_mul_f32_e32 v173, 0x4b800000, v171
	v_cmp_gt_f32_e64 s[0:1], s67, v171
	v_lshl_add_u64 v[224:225], v[152:153], 0, v[188:189]
	s_waitcnt vmcnt(0)
	v_mov_b32_e32 v227, v220
	v_cndmask_b32_e64 v171, v171, v173, s[0:1]
	v_rsq_f32_e32 v171, v171
	v_mov_b32_e32 v220, v219
	v_mov_b32_e32 v226, v218
	v_mul_f32_e32 v152, 0x45800000, v171
	v_cndmask_b32_e64 v190, v171, v152, s[0:1]
	v_pk_mul_f32 v[152:153], v[222:223], v[190:191] op_sel_hi:[1,0]
	v_mov_b32_e32 v222, v210
	v_mov_b32_e32 v223, v212
	v_pk_mul_f32 v[154:155], v[154:155], v[190:191] op_sel_hi:[1,0]
	v_pk_mul_f32 v[152:153], v[222:223], v[152:153]
	v_mov_b32_e32 v223, v216
	v_mov_b32_e32 v212, v211
	v_mov_b32_e32 v216, v215
	v_mov_b32_e32 v222, v214
	v_pk_mul_f32 v[154:155], v[212:213], v[154:155]
	v_pk_add_f32 v[210:211], v[216:217], 1.0 op_sel_hi:[1,0]
	v_pk_add_f32 v[222:223], v[222:223], 1.0 op_sel_hi:[1,0]
	v_pk_fma_f32 v[154:155], v[210:211], v[154:155], v[220:221]
	v_pk_fma_f32 v[152:153], v[222:223], v[152:153], v[226:227]
	v_and_b32_sdwa v175, v155, v205 dst_sel:DWORD dst_unused:UNUSED_PAD src0_sel:WORD_1 src1_sel:DWORD
	v_and_b32_sdwa v210, v154, v205 dst_sel:DWORD dst_unused:UNUSED_PAD src0_sel:WORD_1 src1_sel:DWORD
	v_and_b32_sdwa v171, v153, v205 dst_sel:DWORD dst_unused:UNUSED_PAD src0_sel:WORD_1 src1_sel:DWORD
	v_and_b32_sdwa v173, v152, v205 dst_sel:DWORD dst_unused:UNUSED_PAD src0_sel:WORD_1 src1_sel:DWORD
	v_add3_u32 v175, v155, v175, s80
	v_add3_u32 v210, v154, v210, s80
	v_add3_u32 v173, v152, v173, s80
	v_add3_u32 v171, v153, v171, s80
	v_and_b32_e32 v175, 0xffff0000, v175
	v_and_b32_e32 v210, 0xffff0000, v210
	v_or_b32_sdwa v211, v175, v171 dst_sel:DWORD dst_unused:UNUSED_PAD src0_sel:DWORD src1_sel:WORD_1
	v_or_b32_sdwa v210, v210, v173 dst_sel:DWORD dst_unused:UNUSED_PAD src0_sel:DWORD src1_sel:WORD_1
	v_mov_b32_e32 v250, v224
	v_mov_b32_e32 v251, v225
	v_mov_b32_e32 v252, v210
	v_mov_b32_e32 v253, v211
	v_mov_b32_e32 v171, v161
	global_load_dwordx4 v[210:213], v[164:165], off offset:1024
	v_lshl_add_u64 v[214:215], v[184:185], 0, v[170:171]
	global_load_dwordx4 v[214:217], v[214:215], off
	s_nop 0
	global_load_dwordx4 v[218:221], v[182:183], off offset:1024
	global_store_dwordx2 v[250:251], v[252:253], off
	v_mov_b32_e32 v222, v148
	v_or_b32_e32 v148, v209, v199
	v_mov_b32_e32 v223, v150
	v_mov_b32_e32 v150, v149
	v_ashrrev_i32_e32 v149, 31, v148
	v_lshlrev_b64 v[148:149], 14, v[148:149]
	v_lshl_add_u64 v[148:149], s[62:63], 0, v[148:149]
	v_lshl_add_u64 v[148:149], v[148:149], 0, v[186:187]
	v_lshl_add_u64 v[224:225], v[148:149], 0, v[188:189]
	v_pk_mul_f32 v[148:149], v[222:223], v[190:191] op_sel_hi:[1,0]
	v_pk_mul_f32 v[150:151], v[150:151], v[190:191] op_sel_hi:[1,0]
	v_mov_b32_e32 v173, v161
	v_fma_f32 v230, v7, v152, 0
	v_fmac_f32_e32 v230, v15, v154
	v_fmac_f32_e32 v230, v23, v153
	v_fmac_f32_e32 v230, v155, v31
	s_waitcnt vmcnt(3)
; __device__ __forceinline__ u16 f2bf(float x) { unsigned u = __float_as_uint(x); u += 0x7fffu + ((u >> 16) & 1u); return (u16)(u >> 16); }
; __device__ __forceinline__ size_t a_off(int row, int col, int nks) { return ((size_t)((row >> 8) * nks + (col >> 5)) << 13) + ((row & 255) << 5) + swzc(row, col & 31); }
; template <int MODE>
; __device__ __forceinline__ void norm_phase(const Params& p, const float* src, const float* w, const float* modl, int sh_off, int sc_off,
;                            char* smem, int bid, int nblk) {
;     ...
;         f32x4 sc = *(const f32x4*)(modl + (size_t)b * 6144 + sc_off + c0);
;         f32x4 sh = *(const f32x4*)(modl + (size_t)b * 6144 + sh_off + c0);
; #pragma unroll
;         for (int e = 0; e < 4; ++e) y[e] = v[i][e] * rstd * ww[e] * (1.f + sc[e]) + sh[e];
;         uint2 pk; pk.x = (unsigned)f2bf(y[0]) | ((unsigned)f2bf(y[1]) << 16); pk.y = (unsigned)f2bf(y[2]) | ((unsigned)f2bf(y[3]) << 16);
;         *(uint2*)(hn + a_off(row, c0, 32)) = pk;
;         if (MODE == 1) {
; #pragma unroll
;           for (int e = 0; e < 4; ++e) {
;             f32x4 w0 = *(const f32x4*)(wba + (c0 + e) * 8), w1 = *(const f32x4*)(wba + (c0 + e) * 8 + 4);
; #pragma unroll
;             for (int j = 0; j < 4; ++j) { dots[j] += y[e] * w0[j]; dots[4 + j] += y[e] * w1[j]; }
	v_mov_b32_e32 v222, v210
	v_mov_b32_e32 v223, v212
	s_waitcnt vmcnt(2)
	v_mov_b32_e32 v226, v214
	v_mov_b32_e32 v227, v216
	v_mov_b32_e32 v212, v211
	v_mov_b32_e32 v216, v215
	s_waitcnt vmcnt(1)
	v_mov_b32_e32 v228, v218
	v_mov_b32_e32 v229, v220
	v_mov_b32_e32 v220, v219
	v_pk_mul_f32 v[148:149], v[148:149], v[222:223]
	v_pk_add_f32 v[210:211], v[226:227], 1.0 op_sel_hi:[1,0]
	v_pk_mul_f32 v[212:213], v[150:151], v[212:213]
	v_pk_add_f32 v[214:215], v[216:217], 1.0 op_sel_hi:[1,0]
	v_pk_fma_f32 v[150:151], v[148:149], v[210:211], v[228:229]
	v_pk_fma_f32 v[148:149], v[212:213], v[214:215], v[220:221]
	v_and_b32_sdwa v171, v151, v205 dst_sel:DWORD dst_unused:UNUSED_PAD src0_sel:WORD_1 src1_sel:DWORD
	v_and_b32_sdwa v210, v149, v205 dst_sel:DWORD dst_unused:UNUSED_PAD src0_sel:WORD_1 src1_sel:DWORD
	v_and_b32_sdwa v211, v148, v205 dst_sel:DWORD dst_unused:UNUSED_PAD src0_sel:WORD_1 src1_sel:DWORD
	v_and_b32_sdwa v175, v150, v205 dst_sel:DWORD dst_unused:UNUSED_PAD src0_sel:WORD_1 src1_sel:DWORD
	v_add3_u32 v210, v149, v210, s80
	v_add3_u32 v211, v148, v211, s80
	v_add3_u32 v175, v150, v175, s80
	v_add3_u32 v171, v151, v171, s80
	v_and_b32_e32 v210, 0xffff0000, v210
	v_and_b32_e32 v212, 0xffff0000, v211
	v_or_b32_sdwa v211, v210, v171 dst_sel:DWORD dst_unused:UNUSED_PAD src0_sel:DWORD src1_sel:WORD_1
	v_or_b32_sdwa v210, v212, v175 dst_sel:DWORD dst_unused:UNUSED_PAD src0_sel:DWORD src1_sel:WORD_1
	v_mov_b32_e32 v250, v224
	v_mov_b32_e32 v251, v225
	v_mov_b32_e32 v252, v210
	v_mov_b32_e32 v253, v211
	global_load_dwordx4 v[210:213], v[164:165], off offset:2048
	v_lshl_add_u64 v[214:215], v[184:185], 0, v[172:173]
	global_load_dwordx4 v[214:217], v[214:215], off
	s_nop 0
	global_load_dwordx4 v[218:221], v[182:183], off offset:2048
	global_store_dwordx2 v[250:251], v[252:253], off
	v_mov_b32_e32 v222, v144
	v_mov_b32_e32 v144, v140
	v_or_b32_e32 v140, v209, v200
	v_or_b32_e32 v224, v209, v201
	v_mov_b32_e32 v223, v146
	v_mov_b32_e32 v146, v145
	v_mov_b32_e32 v145, v142
	v_mov_b32_e32 v142, v141
	v_ashrrev_i32_e32 v141, 31, v140
	v_ashrrev_i32_e32 v225, 31, v224
	v_lshlrev_b64 v[140:141], 14, v[140:141]
	v_lshlrev_b64 v[224:225], 14, v[224:225]
	v_lshl_add_u64 v[140:141], s[62:63], 0, v[140:141]
	v_lshl_add_u64 v[224:225], s[62:63], 0, v[224:225]
	v_lshl_add_u64 v[140:141], v[140:141], 0, v[186:187]
	v_lshl_add_u64 v[186:187], v[224:225], 0, v[186:187]
	v_lshl_add_u64 v[224:225], v[140:141], 0, v[188:189]
	v_lshl_add_u64 v[140:141], v[186:187], 0, v[188:189]
	v_pk_mul_f32 v[186:187], v[222:223], v[190:191] op_sel_hi:[1,0]
	v_pk_mul_f32 v[146:147], v[146:147], v[190:191] op_sel_hi:[1,0]
	v_pk_mul_f32 v[188:189], v[144:145], v[190:191] op_sel_hi:[1,0]
	v_pk_mul_f32 v[222:223], v[142:143], v[190:191] op_sel_hi:[1,0]
	v_mov_b32_e32 v175, v161
	v_lshl_add_u64 v[184:185], v[184:185], 0, v[174:175]
	v_fma_f32 v171, v0, v152, 0
	v_fma_f32 v173, v4, v152, 0
	v_fma_f32 v175, v1, v152, 0
	v_fma_f32 v190, v5, v152, 0
	v_fma_f32 v209, v2, v152, 0
	v_fma_f32 v228, v6, v152, 0
	v_fma_f32 v229, v3, v152, 0
	v_fmac_f32_e32 v171, v8, v154
	v_fmac_f32_e32 v173, v12, v154
	v_fmac_f32_e32 v175, v9, v154
	v_fmac_f32_e32 v190, v13, v154
	v_fmac_f32_e32 v209, v10, v154
	v_fmac_f32_e32 v228, v14, v154
	v_fmac_f32_e32 v229, v11, v154
	v_fmac_f32_e32 v171, v16, v153
	v_fmac_f32_e32 v173, v20, v153
	v_fmac_f32_e32 v175, v17, v153
	v_fmac_f32_e32 v190, v21, v153
	v_fmac_f32_e32 v209, v18, v153
	v_fmac_f32_e32 v228, v22, v153
	v_fmac_f32_e32 v229, v19, v153
	v_fmac_f32_e32 v171, v155, v24
	v_fmac_f32_e32 v173, v155, v28
	v_fmac_f32_e32 v175, v155, v25
	v_fmac_f32_e32 v190, v155, v29
	v_fmac_f32_e32 v209, v155, v26
	v_fmac_f32_e32 v228, v155, v30
	v_fmac_f32_e32 v229, v155, v27
	v_fmac_f32_e32 v171, v150, v32
	v_fmac_f32_e32 v173, v150, v36
	v_fmac_f32_e32 v175, v150, v33
	v_fmac_f32_e32 v190, v150, v37
	v_fmac_f32_e32 v209, v150, v34
	v_fmac_f32_e32 v228, v150, v38
	v_fmac_f32_e32 v229, v150, v35
	v_fmac_f32_e32 v230, v150, v39
	v_fmac_f32_e32 v171, v148, v40
	v_fmac_f32_e32 v173, v148, v44
	v_fmac_f32_e32 v175, v148, v41
	v_fmac_f32_e32 v190, v148, v45
	v_fmac_f32_e32 v209, v148, v42
	v_fmac_f32_e32 v228, v148, v46
	v_fmac_f32_e32 v229, v148, v43
	v_fmac_f32_e32 v230, v148, v47
	v_fmac_f32_e32 v171, v151, v48
	v_fmac_f32_e32 v173, v151, v52
	v_fmac_f32_e32 v175, v151, v49
	v_fmac_f32_e32 v190, v151, v53
	v_fmac_f32_e32 v209, v151, v50
	v_fmac_f32_e32 v228, v151, v54
	v_fmac_f32_e32 v229, v151, v51
	v_fmac_f32_e32 v230, v151, v55
	v_fmac_f32_e32 v171, v149, v56
	s_waitcnt vmcnt(3)
	v_mov_b32_e32 v142, v210
	v_mov_b32_e32 v143, v212
	s_waitcnt vmcnt(2)
	v_mov_b32_e32 v144, v214
	v_mov_b32_e32 v145, v216
	v_mov_b32_e32 v212, v211
	v_mov_b32_e32 v216, v215
	s_waitcnt vmcnt(1)
; __device__ __forceinline__ u16 f2bf(float x) { unsigned u = __float_as_uint(x); u += 0x7fffu + ((u >> 16) & 1u); return (u16)(u >> 16); }
; __device__ __forceinline__ size_t a_off(int row, int col, int nks) { return ((size_t)((row >> 8) * nks + (col >> 5)) << 13) + ((row & 255) << 5) + swzc(row, col & 31); }
; template <int MODE>
; __device__ __forceinline__ void norm_phase(const Params& p, const float* src, const float* w, const float* modl, int sh_off, int sc_off,
;                            char* smem, int bid, int nblk) {
;     ...
;         f32x4 sc = *(const f32x4*)(modl + (size_t)b * 6144 + sc_off + c0);
;         f32x4 sh = *(const f32x4*)(modl + (size_t)b * 6144 + sh_off + c0);
; #pragma unroll
;         for (int e = 0; e < 4; ++e) y[e] = v[i][e] * rstd * ww[e] * (1.f + sc[e]) + sh[e];
;         uint2 pk; pk.x = (unsigned)f2bf(y[0]) | ((unsigned)f2bf(y[1]) << 16); pk.y = (unsigned)f2bf(y[2]) | ((unsigned)f2bf(y[3]) << 16);
;         *(uint2*)(hn + a_off(row, c0, 32)) = pk;
;         if (MODE == 1) {
; #pragma unroll
;           for (int e = 0; e < 4; ++e) {
;             f32x4 w0 = *(const f32x4*)(wba + (c0 + e) * 8), w1 = *(const f32x4*)(wba + (c0 + e) * 8 + 4);
; #pragma unroll
;             for (int j = 0; j < 4; ++j) { dots[j] += y[e] * w0[j]; dots[4 + j] += y[e] * w1[j]; }
;           }
;         }
;       }
;     }
;     if (MODE == 1) {
; #pragma unroll
;       for (int j = 0; j < 8; ++j) {
; #pragma unroll
;         for (int o = 32; o >= 1; o >>= 1) dots[j] += __shfl_xor(dots[j], o);
	v_mov_b32_e32 v226, v218
	v_mov_b32_e32 v227, v220
	v_mov_b32_e32 v220, v219
	v_pk_mul_f32 v[142:143], v[186:187], v[142:143]
	v_pk_add_f32 v[144:145], v[144:145], 1.0 op_sel_hi:[1,0]
	v_pk_mul_f32 v[146:147], v[146:147], v[212:213]
	v_pk_add_f32 v[186:187], v[216:217], 1.0 op_sel_hi:[1,0]
	v_pk_fma_f32 v[214:215], v[142:143], v[144:145], v[226:227]
	v_pk_fma_f32 v[146:147], v[146:147], v[186:187], v[220:221]
	v_and_b32_sdwa v143, v214, v205 dst_sel:DWORD dst_unused:UNUSED_PAD src0_sel:WORD_1 src1_sel:DWORD
	v_and_b32_sdwa v144, v147, v205 dst_sel:DWORD dst_unused:UNUSED_PAD src0_sel:WORD_1 src1_sel:DWORD
	v_and_b32_sdwa v145, v146, v205 dst_sel:DWORD dst_unused:UNUSED_PAD src0_sel:WORD_1 src1_sel:DWORD
	v_and_b32_sdwa v142, v215, v205 dst_sel:DWORD dst_unused:UNUSED_PAD src0_sel:WORD_1 src1_sel:DWORD
	v_add3_u32 v152, v214, v143, s80
	v_add3_u32 v143, v147, v144, s80
	v_add3_u32 v144, v146, v145, s80
	v_add3_u32 v142, v215, v142, s80
	v_and_b32_e32 v143, 0xffff0000, v143
	v_and_b32_e32 v144, 0xffff0000, v144
	v_or_b32_sdwa v143, v143, v142 dst_sel:DWORD dst_unused:UNUSED_PAD src0_sel:DWORD src1_sel:WORD_1
	v_or_b32_sdwa v142, v144, v152 dst_sel:DWORD dst_unused:UNUSED_PAD src0_sel:DWORD src1_sel:WORD_1
	v_mov_b32_e32 v250, v224
	v_mov_b32_e32 v251, v225
	v_mov_b32_e32 v252, v142
	v_mov_b32_e32 v253, v143
	global_load_dwordx4 v[142:145], v[164:165], off offset:3072
	v_fmac_f32_e32 v173, v149, v60
	global_load_dwordx4 v[184:187], v[184:185], off
	v_fmac_f32_e32 v175, v149, v57
	global_load_dwordx4 v[210:213], v[182:183], off offset:3072
	global_store_dwordx2 v[250:251], v[252:253], off
	v_fmac_f32_e32 v190, v149, v61
	v_fmac_f32_e32 v209, v149, v58
	v_fmac_f32_e32 v228, v149, v62
	v_fmac_f32_e32 v229, v149, v59
	v_fmac_f32_e32 v230, v149, v63
	v_fmac_f32_e32 v171, v214, v88
	v_fmac_f32_e32 v173, v214, v96
	v_fmac_f32_e32 v175, v214, v89
	v_fmac_f32_e32 v190, v214, v97
	v_fmac_f32_e32 v209, v214, v90
	v_fmac_f32_e32 v228, v214, v98
	v_fmac_f32_e32 v229, v214, v91
	v_fmac_f32_e32 v230, v214, v99
	v_fmac_f32_e32 v171, v146, v64
	v_fmac_f32_e32 v173, v146, v68
	v_fmac_f32_e32 v175, v146, v65
	v_fmac_f32_e32 v190, v146, v69
	v_fmac_f32_e32 v209, v146, v66
	v_fmac_f32_e32 v228, v146, v70
	v_fmac_f32_e32 v229, v146, v67
	v_fmac_f32_e32 v230, v146, v71
	v_fmac_f32_e32 v171, v215, v72
	v_fmac_f32_e32 v173, v215, v76
	v_fmac_f32_e32 v175, v215, v73
	v_fmac_f32_e32 v190, v215, v77
	v_fmac_f32_e32 v209, v215, v74
	v_fmac_f32_e32 v228, v215, v78
	v_fmac_f32_e32 v229, v215, v75
	v_fmac_f32_e32 v230, v215, v79
	v_fmac_f32_e32 v171, v147, v80
	v_fmac_f32_e32 v173, v147, v84
	v_fmac_f32_e32 v175, v147, v81
	v_fmac_f32_e32 v190, v147, v85
	v_fmac_f32_e32 v209, v147, v82
	v_fmac_f32_e32 v228, v147, v86
	v_fmac_f32_e32 v229, v147, v83
	v_fmac_f32_e32 v230, v147, v87
	s_waitcnt vmcnt(3)
	v_mov_b32_e32 v146, v142
	v_mov_b32_e32 v147, v144
	s_waitcnt vmcnt(2)
	v_mov_b32_e32 v148, v184
	v_mov_b32_e32 v149, v186
	s_waitcnt vmcnt(1)
	v_mov_b32_e32 v150, v210
	v_mov_b32_e32 v151, v212
	v_mov_b32_e32 v144, v143
	v_mov_b32_e32 v186, v185
	v_pk_mul_f32 v[142:143], v[188:189], v[146:147]
	v_pk_add_f32 v[146:147], v[148:149], 1.0 op_sel_hi:[1,0]
	v_mov_b32_e32 v212, v211
	v_pk_mul_f32 v[144:145], v[222:223], v[144:145]
	v_pk_add_f32 v[148:149], v[186:187], 1.0 op_sel_hi:[1,0]
	v_pk_fma_f32 v[142:143], v[142:143], v[146:147], v[150:151]
	v_pk_fma_f32 v[144:145], v[144:145], v[148:149], v[212:213]
	v_fmac_f32_e32 v171, v142, v92
	v_fmac_f32_e32 v171, v144, v104
	v_and_b32_sdwa v147, v142, v205 dst_sel:DWORD dst_unused:UNUSED_PAD src0_sel:WORD_1 src1_sel:DWORD
	v_and_b32_sdwa v148, v145, v205 dst_sel:DWORD dst_unused:UNUSED_PAD src0_sel:WORD_1 src1_sel:DWORD
	v_fmac_f32_e32 v171, v143, v112
	v_fmac_f32_e32 v173, v142, v100
	v_fmac_f32_e32 v175, v142, v93
	v_fmac_f32_e32 v190, v142, v101
	v_fmac_f32_e32 v209, v142, v94
	v_fmac_f32_e32 v228, v142, v102
	v_fmac_f32_e32 v229, v142, v95
	v_fmac_f32_e32 v230, v142, v103
	v_add3_u32 v182, v142, v147, s80
	v_add3_u32 v142, v145, v148, s80
	v_fmac_f32_e32 v171, v145, v120
	v_and_b32_e32 v185, 0xffff0000, v142
	ds_bpermute_b32 v142, v159, v171
	v_and_b32_sdwa v149, v144, v205 dst_sel:DWORD dst_unused:UNUSED_PAD src0_sel:WORD_1 src1_sel:DWORD
	v_add3_u32 v184, v144, v149, s80
	v_fmac_f32_e32 v173, v144, v108
	v_fmac_f32_e32 v175, v144, v105
	s_waitcnt lgkmcnt(0)
	v_add_f32_e32 v142, v171, v142
	v_fmac_f32_e32 v190, v144, v109
	v_fmac_f32_e32 v209, v144, v106
	v_fmac_f32_e32 v228, v144, v110
	v_fmac_f32_e32 v229, v144, v107
	v_fmac_f32_e32 v230, v144, v111
	ds_bpermute_b32 v144, v191, v142
	v_fmac_f32_e32 v175, v143, v113
	v_and_b32_sdwa v146, v143, v205 dst_sel:DWORD dst_unused:UNUSED_PAD src0_sel:WORD_1 src1_sel:DWORD
	v_fmac_f32_e32 v175, v145, v121
	v_add3_u32 v183, v143, v146, s80
	v_fmac_f32_e32 v173, v143, v116
	v_fmac_f32_e32 v190, v143, v117
	v_fmac_f32_e32 v209, v143, v114
	v_fmac_f32_e32 v228, v143, v118
	v_fmac_f32_e32 v229, v143, v115
	v_fmac_f32_e32 v230, v143, v119
	ds_bpermute_b32 v143, v159, v175
	s_waitcnt lgkmcnt(1)
	v_add_f32_e32 v142, v142, v144
	ds_bpermute_b32 v144, v192, v142
	v_fmac_f32_e32 v209, v145, v122
	ds_bpermute_b32 v147, v159, v209
	s_waitcnt lgkmcnt(2)
	v_add_f32_e32 v143, v175, v143
	ds_bpermute_b32 v146, v191, v143
	s_waitcnt lgkmcnt(2)
	v_add_f32_e32 v142, v142, v144
	ds_bpermute_b32 v144, v193, v142
	s_waitcnt lgkmcnt(2)
	v_add_f32_e32 v147, v209, v147
	ds_bpermute_b32 v148, v191, v147
	s_waitcnt lgkmcnt(2)
	v_add_f32_e32 v143, v143, v146
	ds_bpermute_b32 v146, v192, v143
	s_waitcnt lgkmcnt(2)
	v_add_f32_e32 v142, v142, v144
	ds_bpermute_b32 v144, v194, v142
	v_fmac_f32_e32 v173, v145, v124
	s_waitcnt lgkmcnt(2)
; __device__ __forceinline__ float sigmoid_(float x) { return __builtin_amdgcn_rcpf(1.f + __expf(-x)); }
; __device__ __forceinline__ float softplus_(float x) { return fmaxf(x, 0.f) + log1pf(__expf(-fabsf(x))); }
; template <int MODE>
; __device__ __forceinline__ void norm_phase(const Params& p, const float* src, const float* w, const float* modl, int sh_off, int sc_off,
;                            char* smem, int bid, int nblk) {
;     ...
;     if (MODE == 1) {
; #pragma unroll
;       for (int j = 0; j < 8; ++j) {
; #pragma unroll
;         for (int o = 32; o >= 1; o >>= 1) dots[j] += __shfl_xor(dots[j], o);
;       }
;       if (lane == 0) {
;         float* beta = (float*)(p.ws + OFF_BETA); float* gg = (float*)(p.ws + OFF_G);
; #pragma unroll
;         for (int h = 0; h < 4; ++h) {
;           beta[(size_t)row * 4 + h] = sigmoid_(dots[h]);
;           gg[(size_t)row * 4 + h] = -__expf(p.hy_a_log[h]) * softplus_(dots[4 + h] + p.hy_dt_bias[h]);
;         }
	v_add_f32_e32 v147, v147, v148
	s_waitcnt lgkmcnt(1)
	v_add_f32_e32 v143, v143, v146
	ds_bpermute_b32 v146, v193, v143
	s_waitcnt lgkmcnt(1)
	v_add_f32_e32 v154, v142, v144
	ds_bpermute_b32 v144, v159, v173
	ds_bpermute_b32 v142, v192, v147
	v_fmac_f32_e32 v229, v145, v123
	s_waitcnt lgkmcnt(2)
	v_add_f32_e32 v143, v143, v146
	v_fmac_f32_e32 v190, v145, v125
	s_waitcnt lgkmcnt(1)
	v_add_f32_e32 v144, v173, v144
	v_fmac_f32_e32 v228, v145, v126
	v_fmac_f32_e32 v230, v145, v127
	ds_bpermute_b32 v145, v159, v229
	ds_bpermute_b32 v146, v194, v143
	s_waitcnt lgkmcnt(2)
	v_add_f32_e32 v142, v147, v142
	ds_bpermute_b32 v147, v191, v144
	ds_bpermute_b32 v149, v193, v142
	s_waitcnt lgkmcnt(3)
	v_add_f32_e32 v145, v229, v145
	s_waitcnt lgkmcnt(2)
	v_add_f32_e32 v171, v143, v146
	ds_bpermute_b32 v148, v191, v145
	s_waitcnt lgkmcnt(2)
	v_add_f32_e32 v143, v144, v147
	ds_bpermute_b32 v144, v192, v143
	s_waitcnt lgkmcnt(2)
	v_add_f32_e32 v142, v142, v149
	ds_bpermute_b32 v147, v194, v142
	s_waitcnt lgkmcnt(2)
	v_add_f32_e32 v145, v145, v148
	ds_bpermute_b32 v148, v192, v145
	s_waitcnt lgkmcnt(2)
	v_add_f32_e32 v143, v143, v144
	ds_bpermute_b32 v144, v193, v143
	s_waitcnt lgkmcnt(2)
	v_add_f32_e32 v150, v142, v147
	ds_bpermute_b32 v155, v195, v154
	s_waitcnt lgkmcnt(2)
	v_add_f32_e32 v145, v145, v148
	ds_bpermute_b32 v146, v193, v145
	s_waitcnt lgkmcnt(2)
	v_add_f32_e32 v142, v143, v144
	ds_bpermute_b32 v143, v194, v142
	ds_bpermute_b32 v144, v159, v190
	ds_bpermute_b32 v173, v195, v171
	s_waitcnt lgkmcnt(3)
	v_add_f32_e32 v145, v145, v146
	ds_bpermute_b32 v146, v194, v145
	s_waitcnt lgkmcnt(3)
	v_add_f32_e32 v152, v142, v143
	ds_bpermute_b32 v142, v159, v228
	ds_bpermute_b32 v143, v159, v230
	s_waitcnt lgkmcnt(4)
	v_add_f32_e32 v144, v190, v144
	s_waitcnt lgkmcnt(2)
	v_add_f32_e32 v146, v145, v146
	ds_bpermute_b32 v145, v191, v144
	s_waitcnt lgkmcnt(2)
	v_add_f32_e32 v142, v228, v142
	s_waitcnt lgkmcnt(1)
	v_add_f32_e32 v143, v230, v143
	ds_bpermute_b32 v148, v191, v142
	ds_bpermute_b32 v149, v191, v143
	s_waitcnt lgkmcnt(2)
	v_add_f32_e32 v144, v144, v145
	ds_bpermute_b32 v145, v192, v144
	ds_bpermute_b32 v151, v195, v150
	s_waitcnt lgkmcnt(3)
	v_add_f32_e32 v142, v142, v148
	s_waitcnt lgkmcnt(2)
	v_add_f32_e32 v143, v143, v149
	ds_bpermute_b32 v148, v192, v142
	ds_bpermute_b32 v149, v192, v143
	s_waitcnt lgkmcnt(3)
	v_add_f32_e32 v144, v144, v145
	ds_bpermute_b32 v145, v193, v144
	ds_bpermute_b32 v147, v195, v146
	s_waitcnt lgkmcnt(3)
	v_add_f32_e32 v142, v142, v148
	s_waitcnt lgkmcnt(2)
	v_add_f32_e32 v143, v143, v149
	ds_bpermute_b32 v148, v193, v142
	ds_bpermute_b32 v149, v193, v143
	s_waitcnt lgkmcnt(3)
	v_add_f32_e32 v144, v144, v145
	ds_bpermute_b32 v145, v194, v144
	ds_bpermute_b32 v153, v195, v152
	s_waitcnt lgkmcnt(3)
	v_add_f32_e32 v142, v142, v148
	s_waitcnt lgkmcnt(2)
	v_add_f32_e32 v143, v143, v149
	ds_bpermute_b32 v175, v194, v142
	ds_bpermute_b32 v186, v194, v143
	s_waitcnt lgkmcnt(3)
	v_add_f32_e32 v148, v144, v145
	ds_bpermute_b32 v149, v195, v148
	v_or_b32_sdwa v183, v185, v183 dst_sel:DWORD dst_unused:UNUSED_PAD src0_sel:DWORD src1_sel:WORD_1
	s_waitcnt lgkmcnt(2)
	v_add_f32_e32 v144, v142, v175
	s_waitcnt lgkmcnt(1)
	v_add_f32_e32 v142, v143, v186
	ds_bpermute_b32 v145, v195, v144
	ds_bpermute_b32 v143, v195, v142
	v_and_b32_e32 v175, 0xffff0000, v184
	v_or_b32_sdwa v182, v175, v182 dst_sel:DWORD dst_unused:UNUSED_PAD src0_sel:DWORD src1_sel:WORD_1
	global_store_dwordx2 v[140:141], v[182:183], off
	s_and_saveexec_b64 s[0:1], vcc
	s_xor_b64 s[64:65], exec, s[0:1]
	s_cbranch_execz .LBB0_109
	v_add_f32_e32 v140, v154, v155
	v_mul_f32_e32 v140, 0xbfb8aa3b, v140
	v_exp_f32_e32 v140, v140
	v_add_f32_e32 v152, v152, v153
	v_add_f32_e32 v150, v150, v151
	v_mul_f32_e32 v150, 0xbfb8aa3b, v150
	v_add_f32_e32 v140, 1.0, v140
	v_rcp_f32_e32 v140, v140
	v_exp_f32_e32 v150, v150
	s_waitcnt lgkmcnt(2)
	v_add_f32_e32 v148, v148, v149
	v_add_f32_e32 v146, v146, v147
	global_store_dword v[166:167], v140, off
	global_load_dword v154, v161, s[58:59]
	global_load_dword v155, v161, s[56:57]
	v_add_f32_e32 v140, v171, v173
	v_mul_f32_e32 v140, 0xbfb8aa3b, v140
	v_exp_f32_e32 v140, v140
	v_add_f32_e32 v150, 1.0, v150
	v_rcp_f32_e32 v150, v150
	v_mul_f32_e32 v146, 0xbfb8aa3b, v146
	v_add_f32_e32 v140, 1.0, v140
	v_rcp_f32_e32 v153, v140
	v_add_co_u32_e64 v140, s[0:1], s86, v166
	v_exp_f32_e32 v146, v146
	global_store_dword v[166:167], v153, off offset:4
	v_addc_co_u32_e64 v141, s[0:1], 0, v167, s[0:1]
	v_add_f32_e32 v146, 1.0, v146
	v_rcp_f32_e32 v146, v146
	s_waitcnt lgkmcnt(1)
	v_add_f32_e32 v144, v144, v145
	s_waitcnt lgkmcnt(0)
	v_add_f32_e32 v142, v142, v143
	s_waitcnt vmcnt(2)
	v_add_f32_e32 v152, v152, v154
	v_mul_f32_e64 v153, |v152|, s81
	v_exp_f32_e32 v154, v153
	s_waitcnt vmcnt(1)
; __device__ __forceinline__ float sigmoid_(float x) { return __builtin_amdgcn_rcpf(1.f + __expf(-x)); }
; __device__ __forceinline__ float softplus_(float x) { return fmaxf(x, 0.f) + log1pf(__expf(-fabsf(x))); }
; template <int MODE>
; __device__ __forceinline__ void norm_phase(const Params& p, const float* src, const float* w, const float* modl, int sh_off, int sc_off,
;                            char* smem, int bid, int nblk) {
;     ...
;         float* beta = (float*)(p.ws + OFF_BETA); float* gg = (float*)(p.ws + OFF_G);
; #pragma unroll
;         for (int h = 0; h < 4; ++h) {
;           beta[(size_t)row * 4 + h] = sigmoid_(dots[h]);
;           gg[(size_t)row * 4 + h] = -__expf(p.hy_a_log[h]) * softplus_(dots[4 + h] + p.hy_dt_bias[h]);
;         }
	v_mul_f32_e32 v153, 0x3fb8aa3b, v155
	v_exp_f32_e32 v155, v153
	v_max_f32_e32 v171, 0, v152
	v_add_f32_e32 v173, 1.0, v154
	v_add_f32_e32 v175, -1.0, v173
	v_frexp_mant_f32_e32 v182, v173
	v_cvt_f64_f32_e32 v[152:153], v173
	v_sub_f32_e32 v183, v175, v173
	v_frexp_exp_i32_f64_e32 v152, v[152:153]
	v_cmp_gt_f32_e64 s[0:1], s82, v182
	v_sub_f32_e32 v175, v154, v175
	v_add_f32_e32 v153, 1.0, v183
	v_subbrev_co_u32_e64 v152, s[0:1], 0, v152, s[0:1]
	v_add_f32_e32 v153, v175, v153
	v_sub_u32_e32 v175, 0, v152
	v_cvt_f32_i32_e32 v152, v152
	v_ldexp_f32 v173, v173, v175
	v_ldexp_f32 v153, v153, v175
	v_add_f32_e32 v175, -1.0, v173
	v_add_f32_e32 v182, 1.0, v173
	v_add_f32_e32 v183, 1.0, v175
	v_add_f32_e32 v184, -1.0, v182
	v_sub_f32_e32 v183, v173, v183
	v_sub_f32_e32 v173, v173, v184
	v_mul_f32_e32 v184, 0x3f317218, v152
	v_add_f32_e32 v183, v153, v183
	v_add_f32_e32 v153, v153, v173
	v_fma_f32 v173, v152, s83, -v184
	v_add_f32_e32 v185, v175, v183
	v_add_f32_e32 v186, v182, v153
	v_fmac_f32_e32 v173, 0xb102e308, v152
	v_sub_f32_e32 v152, v185, v175
	v_sub_f32_e32 v175, v186, v182
	v_rcp_f32_e32 v182, v186
	v_add_f32_e32 v187, v184, v173
	v_sub_f32_e32 v153, v153, v175
	v_sub_f32_e32 v175, v187, v184
	v_sub_f32_e32 v173, v173, v175
	v_mul_f32_e32 v175, v185, v182
	v_sub_f32_e32 v152, v183, v152
	v_mul_f32_e32 v183, v186, v175
	v_fma_f32 v184, v175, v186, -v183
	v_fmac_f32_e32 v184, v175, v153
	v_add_f32_e32 v188, v183, v184
	v_sub_f32_e32 v189, v185, v188
	v_sub_f32_e32 v183, v188, v183
	v_sub_f32_e32 v185, v185, v189
	v_sub_f32_e32 v183, v183, v184
	v_sub_f32_e32 v184, v185, v188
	v_add_f32_e32 v152, v152, v184
	v_add_f32_e32 v152, v183, v152
	v_add_f32_e32 v183, v189, v152
	v_mul_f32_e32 v184, v182, v183
	v_sub_f32_e32 v185, v189, v183
	v_mul_f32_e32 v188, v186, v184
	v_add_f32_e32 v152, v152, v185
	v_add_f32_e32 v185, v175, v184
	v_fma_f32 v186, v184, v186, -v188
	v_sub_f32_e32 v175, v185, v175
	v_fmac_f32_e32 v186, v184, v153
	v_sub_f32_e32 v153, v184, v175
	v_add_f32_e32 v175, v188, v186
	v_sub_f32_e32 v184, v175, v188
	v_sub_f32_e32 v188, v183, v175
	v_sub_f32_e32 v183, v183, v188
	v_sub_f32_e32 v175, v183, v175
	v_sub_f32_e32 v184, v184, v186
	v_add_f32_e32 v152, v152, v175
	v_add_f32_e32 v152, v184, v152
	v_add_f32_e32 v152, v188, v152
	v_mul_f32_e32 v152, v182, v152
	v_add_f32_e32 v152, v153, v152
	v_add_f32_e32 v153, v185, v152
	v_mul_f32_e32 v175, v153, v153
	v_fmamk_f32 v184, v175, 0x3e9b6dac, v204
	v_sub_f32_e32 v182, v153, v185
	v_ldexp_f32 v183, v153, 1
	v_mul_f32_e32 v153, v153, v175
	v_fmaak_f32 v175, v175, v184, 0x3f2aaada
	v_mul_f32_e32 v153, v153, v175
	v_add_f32_e32 v175, v183, v153
	v_sub_f32_e32 v152, v152, v182
	v_sub_f32_e32 v182, v175, v183
	v_ldexp_f32 v152, v152, 1
	v_sub_f32_e32 v153, v153, v182
	v_add_f32_e32 v152, v152, v153
	v_add_f32_e32 v153, v175, v152
	v_sub_f32_e32 v175, v153, v175
	v_add_f32_e32 v182, v187, v153
	v_sub_f32_e32 v152, v152, v175
	v_sub_f32_e32 v175, v182, v187
	v_sub_f32_e32 v183, v182, v175
	v_sub_f32_e32 v153, v153, v175
	v_add_f32_e32 v175, v173, v152
	v_sub_f32_e32 v183, v187, v183
	v_sub_f32_e32 v184, v175, v173
	v_add_f32_e32 v153, v153, v183
	v_sub_f32_e32 v183, v175, v184
	v_sub_f32_e32 v152, v152, v184
	v_sub_f32_e32 v173, v173, v183
	v_add_f32_e32 v153, v175, v153
	v_add_f32_e32 v152, v152, v173
	v_add_f32_e32 v173, v182, v153
	v_sub_f32_e32 v175, v173, v182
	v_sub_f32_e32 v153, v153, v175
	v_add_f32_e32 v152, v152, v153
	v_add_f32_e32 v152, v173, v152
	v_cmp_neq_f32_e64 s[0:1], s84, v154
	s_nop 1
	v_cndmask_b32_e64 v152, v206, v152, s[0:1]
	v_cmp_ngt_f32_e64 s[0:1], -1.0, v154
	s_nop 1
	v_cndmask_b32_e64 v152, v207, v152, s[0:1]
	v_cmp_neq_f32_e64 s[0:1], -1.0, v154
	s_nop 1
	v_cndmask_b32_e64 v152, v208, v152, s[0:1]
	v_cmp_lt_f32_e64 s[0:1], |v154|, s85
	s_nop 1
	v_cndmask_b32_e64 v152, v152, v154, s[0:1]
	v_add_f32_e32 v152, v171, v152
	v_mul_f32_e64 v152, v152, -v155
	global_store_dword v[140:141], v152, off
	global_load_dword v152, v161, s[58:59] offset:4
	s_nop 0
	global_load_dword v153, v161, s[56:57] offset:4
	s_waitcnt vmcnt(1)
	v_add_f32_e32 v148, v148, v152
	v_mul_f32_e64 v149, |v148|, s81
	global_store_dword v[166:167], v150, off offset:8
	v_exp_f32_e32 v150, v149
	s_waitcnt vmcnt(1)
; __device__ __forceinline__ float sigmoid_(float x) { return __builtin_amdgcn_rcpf(1.f + __expf(-x)); }
; __device__ __forceinline__ float softplus_(float x) { return fmaxf(x, 0.f) + log1pf(__expf(-fabsf(x))); }
; template <int MODE>
; __device__ __forceinline__ void norm_phase(const Params& p, const float* src, const float* w, const float* modl, int sh_off, int sc_off,
;                            char* smem, int bid, int nblk) {
;     ...
;         float* beta = (float*)(p.ws + OFF_BETA); float* gg = (float*)(p.ws + OFF_G);
; #pragma unroll
;         for (int h = 0; h < 4; ++h) {
;           beta[(size_t)row * 4 + h] = sigmoid_(dots[h]);
;           gg[(size_t)row * 4 + h] = -__expf(p.hy_a_log[h]) * softplus_(dots[4 + h] + p.hy_dt_bias[h]);
;         }
	v_mul_f32_e32 v149, 0x3fb8aa3b, v153
	v_exp_f32_e32 v151, v149
	v_max_f32_e32 v152, 0, v148
	v_add_f32_e32 v153, 1.0, v150
	v_add_f32_e32 v154, -1.0, v153
	v_frexp_mant_f32_e32 v155, v153
	v_cvt_f64_f32_e32 v[148:149], v153
	v_sub_f32_e32 v171, v154, v153
	v_frexp_exp_i32_f64_e32 v148, v[148:149]
	v_cmp_gt_f32_e64 s[0:1], s82, v155
	v_sub_f32_e32 v154, v150, v154
	v_add_f32_e32 v149, 1.0, v171
	v_subbrev_co_u32_e64 v148, s[0:1], 0, v148, s[0:1]
	v_add_f32_e32 v149, v154, v149
	v_sub_u32_e32 v154, 0, v148
	v_cvt_f32_i32_e32 v148, v148
	v_ldexp_f32 v153, v153, v154
	v_ldexp_f32 v149, v149, v154
	v_add_f32_e32 v154, -1.0, v153
	v_add_f32_e32 v155, 1.0, v153
	v_add_f32_e32 v171, 1.0, v154
	v_add_f32_e32 v173, -1.0, v155
	v_sub_f32_e32 v171, v153, v171
	v_sub_f32_e32 v153, v153, v173
	v_mul_f32_e32 v173, 0x3f317218, v148
	v_add_f32_e32 v171, v149, v171
	v_add_f32_e32 v149, v149, v153
	v_fma_f32 v153, v148, s83, -v173
	v_add_f32_e32 v175, v154, v171
	v_add_f32_e32 v182, v155, v149
	v_fmac_f32_e32 v153, 0xb102e308, v148
	v_sub_f32_e32 v148, v175, v154
	v_sub_f32_e32 v154, v182, v155
	v_rcp_f32_e32 v155, v182
	v_add_f32_e32 v183, v173, v153
	v_sub_f32_e32 v149, v149, v154
	v_sub_f32_e32 v154, v183, v173
	v_sub_f32_e32 v153, v153, v154
	v_mul_f32_e32 v154, v175, v155
	v_sub_f32_e32 v148, v171, v148
	v_mul_f32_e32 v171, v182, v154
	v_fma_f32 v173, v154, v182, -v171
	v_fmac_f32_e32 v173, v154, v149
	v_add_f32_e32 v184, v171, v173
	v_sub_f32_e32 v185, v175, v184
	v_sub_f32_e32 v171, v184, v171
	v_sub_f32_e32 v175, v175, v185
	v_sub_f32_e32 v171, v171, v173
	v_sub_f32_e32 v173, v175, v184
	v_add_f32_e32 v148, v148, v173
	v_add_f32_e32 v148, v171, v148
	v_add_f32_e32 v171, v185, v148
	v_mul_f32_e32 v173, v155, v171
	v_sub_f32_e32 v175, v185, v171
	v_mul_f32_e32 v184, v182, v173
	v_add_f32_e32 v148, v148, v175
	v_add_f32_e32 v175, v154, v173
	v_fma_f32 v182, v173, v182, -v184
	v_sub_f32_e32 v154, v175, v154
	v_fmac_f32_e32 v182, v173, v149
	v_sub_f32_e32 v149, v173, v154
	v_add_f32_e32 v154, v184, v182
	v_sub_f32_e32 v173, v154, v184
	v_sub_f32_e32 v184, v171, v154
	v_sub_f32_e32 v171, v171, v184
	v_sub_f32_e32 v154, v171, v154
	v_sub_f32_e32 v173, v173, v182
	v_add_f32_e32 v148, v148, v154
	v_add_f32_e32 v148, v173, v148
	v_add_f32_e32 v148, v184, v148
	v_mul_f32_e32 v148, v155, v148
	v_add_f32_e32 v148, v149, v148
	v_add_f32_e32 v149, v175, v148
	v_mul_f32_e32 v154, v149, v149
	v_fmamk_f32 v173, v154, 0x3e9b6dac, v204
	v_sub_f32_e32 v155, v149, v175
	v_ldexp_f32 v171, v149, 1
	v_mul_f32_e32 v149, v149, v154
	v_fmaak_f32 v154, v154, v173, 0x3f2aaada
	v_mul_f32_e32 v149, v149, v154
	v_add_f32_e32 v154, v171, v149
	v_sub_f32_e32 v148, v148, v155
	v_sub_f32_e32 v155, v154, v171
	v_ldexp_f32 v148, v148, 1
	v_sub_f32_e32 v149, v149, v155
	v_add_f32_e32 v148, v148, v149
	v_add_f32_e32 v149, v154, v148
	v_sub_f32_e32 v154, v149, v154
	v_add_f32_e32 v155, v183, v149
	v_sub_f32_e32 v148, v148, v154
	v_sub_f32_e32 v154, v155, v183
	v_sub_f32_e32 v171, v155, v154
	v_sub_f32_e32 v149, v149, v154
	v_add_f32_e32 v154, v153, v148
	v_sub_f32_e32 v171, v183, v171
	v_sub_f32_e32 v173, v154, v153
	v_add_f32_e32 v149, v149, v171
	v_sub_f32_e32 v171, v154, v173
	v_sub_f32_e32 v148, v148, v173
	v_sub_f32_e32 v153, v153, v171
	v_add_f32_e32 v149, v154, v149
	v_add_f32_e32 v148, v148, v153
	v_add_f32_e32 v153, v155, v149
	v_sub_f32_e32 v154, v153, v155
	v_sub_f32_e32 v149, v149, v154
	v_add_f32_e32 v148, v148, v149
	v_add_f32_e32 v148, v153, v148
	v_cmp_neq_f32_e64 s[0:1], s84, v150
	s_nop 1
	v_cndmask_b32_e64 v148, v206, v148, s[0:1]
	v_cmp_ngt_f32_e64 s[0:1], -1.0, v150
	s_nop 1
	v_cndmask_b32_e64 v148, v207, v148, s[0:1]
	v_cmp_neq_f32_e64 s[0:1], -1.0, v150
	s_nop 1
	v_cndmask_b32_e64 v148, v208, v148, s[0:1]
	v_cmp_lt_f32_e64 s[0:1], |v150|, s85
	s_nop 1
	v_cndmask_b32_e64 v148, v148, v150, s[0:1]
	v_add_f32_e32 v148, v152, v148
	v_mul_f32_e64 v148, v148, -v151
	global_store_dword v[140:141], v148, off offset:4
	global_load_dword v148, v161, s[58:59] offset:8
	s_nop 0
	global_load_dword v149, v161, s[56:57] offset:8
	s_waitcnt vmcnt(1)
	v_add_f32_e32 v144, v144, v148
	v_mul_f32_e64 v145, |v144|, s81
	global_store_dword v[166:167], v146, off offset:12
	v_exp_f32_e32 v146, v145
	s_waitcnt vmcnt(1)
; __device__ __forceinline__ float sigmoid_(float x) { return __builtin_amdgcn_rcpf(1.f + __expf(-x)); }
; __device__ __forceinline__ float softplus_(float x) { return fmaxf(x, 0.f) + log1pf(__expf(-fabsf(x))); }
; template <int MODE>
; __device__ __forceinline__ void norm_phase(const Params& p, const float* src, const float* w, const float* modl, int sh_off, int sc_off,
;                            char* smem, int bid, int nblk) {
;     ...
;         float* beta = (float*)(p.ws + OFF_BETA); float* gg = (float*)(p.ws + OFF_G);
; #pragma unroll
;         for (int h = 0; h < 4; ++h) {
;           beta[(size_t)row * 4 + h] = sigmoid_(dots[h]);
;           gg[(size_t)row * 4 + h] = -__expf(p.hy_a_log[h]) * softplus_(dots[4 + h] + p.hy_dt_bias[h]);
;         }
	v_mul_f32_e32 v145, 0x3fb8aa3b, v149
	v_exp_f32_e32 v147, v145
	v_max_f32_e32 v148, 0, v144
	v_add_f32_e32 v149, 1.0, v146
	v_add_f32_e32 v150, -1.0, v149
	v_frexp_mant_f32_e32 v151, v149
	v_cvt_f64_f32_e32 v[144:145], v149
	v_sub_f32_e32 v152, v150, v149
	v_frexp_exp_i32_f64_e32 v144, v[144:145]
	v_cmp_gt_f32_e64 s[0:1], s82, v151
	v_sub_f32_e32 v150, v146, v150
	v_add_f32_e32 v145, 1.0, v152
	v_subbrev_co_u32_e64 v144, s[0:1], 0, v144, s[0:1]
	v_add_f32_e32 v145, v150, v145
	v_sub_u32_e32 v150, 0, v144
	v_cvt_f32_i32_e32 v144, v144
	v_ldexp_f32 v149, v149, v150
	v_ldexp_f32 v145, v145, v150
	v_add_f32_e32 v150, -1.0, v149
	v_add_f32_e32 v151, 1.0, v149
	v_add_f32_e32 v152, 1.0, v150
	v_add_f32_e32 v153, -1.0, v151
	v_sub_f32_e32 v152, v149, v152
	v_sub_f32_e32 v149, v149, v153
	v_mul_f32_e32 v153, 0x3f317218, v144
	v_add_f32_e32 v152, v145, v152
	v_add_f32_e32 v145, v145, v149
	v_fma_f32 v149, v144, s83, -v153
	v_add_f32_e32 v154, v150, v152
	v_add_f32_e32 v155, v151, v145
	v_fmac_f32_e32 v149, 0xb102e308, v144
	v_sub_f32_e32 v144, v154, v150
	v_sub_f32_e32 v150, v155, v151
	v_rcp_f32_e32 v151, v155
	v_add_f32_e32 v171, v153, v149
	v_sub_f32_e32 v145, v145, v150
	v_sub_f32_e32 v150, v171, v153
	v_sub_f32_e32 v149, v149, v150
	v_mul_f32_e32 v150, v154, v151
	v_sub_f32_e32 v144, v152, v144
	v_mul_f32_e32 v152, v155, v150
	v_fma_f32 v153, v150, v155, -v152
	v_fmac_f32_e32 v153, v150, v145
	v_add_f32_e32 v173, v152, v153
	v_sub_f32_e32 v175, v154, v173
	v_sub_f32_e32 v152, v173, v152
	v_sub_f32_e32 v154, v154, v175
	v_sub_f32_e32 v152, v152, v153
	v_sub_f32_e32 v153, v154, v173
	v_add_f32_e32 v144, v144, v153
	v_add_f32_e32 v144, v152, v144
	v_add_f32_e32 v152, v175, v144
	v_mul_f32_e32 v153, v151, v152
	v_sub_f32_e32 v154, v175, v152
	v_mul_f32_e32 v173, v155, v153
	v_add_f32_e32 v144, v144, v154
	v_add_f32_e32 v154, v150, v153
	v_fma_f32 v155, v153, v155, -v173
	v_sub_f32_e32 v150, v154, v150
	v_fmac_f32_e32 v155, v153, v145
	v_sub_f32_e32 v145, v153, v150
	v_add_f32_e32 v150, v173, v155
	v_sub_f32_e32 v153, v150, v173
	v_sub_f32_e32 v173, v152, v150
	v_sub_f32_e32 v152, v152, v173
	v_sub_f32_e32 v150, v152, v150
	v_sub_f32_e32 v153, v153, v155
	v_add_f32_e32 v144, v144, v150
	v_add_f32_e32 v144, v153, v144
	v_add_f32_e32 v144, v173, v144
	v_mul_f32_e32 v144, v151, v144
	v_add_f32_e32 v144, v145, v144
	v_add_f32_e32 v145, v154, v144
	v_mul_f32_e32 v150, v145, v145
	v_fmamk_f32 v153, v150, 0x3e9b6dac, v204
	v_sub_f32_e32 v151, v145, v154
	v_ldexp_f32 v152, v145, 1
	v_mul_f32_e32 v145, v145, v150
	v_fmaak_f32 v150, v150, v153, 0x3f2aaada
	v_mul_f32_e32 v145, v145, v150
	v_add_f32_e32 v150, v152, v145
	v_sub_f32_e32 v144, v144, v151
	v_sub_f32_e32 v151, v150, v152
	v_ldexp_f32 v144, v144, 1
	v_sub_f32_e32 v145, v145, v151
	v_add_f32_e32 v144, v144, v145
	v_add_f32_e32 v145, v150, v144
	v_sub_f32_e32 v150, v145, v150
	v_add_f32_e32 v151, v171, v145
	v_sub_f32_e32 v144, v144, v150
	v_sub_f32_e32 v150, v151, v171
	v_sub_f32_e32 v152, v151, v150
	v_sub_f32_e32 v145, v145, v150
	v_add_f32_e32 v150, v149, v144
	v_sub_f32_e32 v152, v171, v152
	v_sub_f32_e32 v153, v150, v149
	v_add_f32_e32 v145, v145, v152
	v_sub_f32_e32 v152, v150, v153
	v_sub_f32_e32 v144, v144, v153
	v_sub_f32_e32 v149, v149, v152
	v_add_f32_e32 v145, v150, v145
	v_add_f32_e32 v144, v144, v149
	v_add_f32_e32 v149, v151, v145
	v_sub_f32_e32 v150, v149, v151
	v_sub_f32_e32 v145, v145, v150
	v_add_f32_e32 v144, v144, v145
	v_add_f32_e32 v144, v149, v144
	v_cmp_neq_f32_e64 s[0:1], s84, v146
	s_nop 1
	v_cndmask_b32_e64 v144, v206, v144, s[0:1]
	v_cmp_ngt_f32_e64 s[0:1], -1.0, v146
	s_nop 1
	v_cndmask_b32_e64 v144, v207, v144, s[0:1]
	v_cmp_neq_f32_e64 s[0:1], -1.0, v146
	s_nop 1
	v_cndmask_b32_e64 v144, v208, v144, s[0:1]
	v_cmp_lt_f32_e64 s[0:1], |v146|, s85
	s_nop 1
	v_cndmask_b32_e64 v144, v144, v146, s[0:1]
	v_add_f32_e32 v144, v148, v144
	v_mul_f32_e64 v144, v144, -v147
	global_store_dword v[140:141], v144, off offset:8
	global_load_dword v144, v161, s[58:59] offset:12
	s_nop 0
	global_load_dword v145, v161, s[56:57] offset:12
	s_waitcnt vmcnt(1)
; __device__ __forceinline__ float sigmoid_(float x) { return __builtin_amdgcn_rcpf(1.f + __expf(-x)); }
; __device__ __forceinline__ float softplus_(float x) { return fmaxf(x, 0.f) + log1pf(__expf(-fabsf(x))); }
; template <int MODE>
; __device__ __forceinline__ void norm_phase(const Params& p, const float* src, const float* w, const float* modl, int sh_off, int sc_off,
;                            char* smem, int bid, int nblk) {
;     ...
;         float* beta = (float*)(p.ws + OFF_BETA); float* gg = (float*)(p.ws + OFF_G);
; #pragma unroll
;         for (int h = 0; h < 4; ++h) {
;           beta[(size_t)row * 4 + h] = sigmoid_(dots[h]);
;           gg[(size_t)row * 4 + h] = -__expf(p.hy_a_log[h]) * softplus_(dots[4 + h] + p.hy_dt_bias[h]);
;         }
	v_add_f32_e32 v142, v142, v144
	v_mul_f32_e64 v143, |v142|, s81
	v_exp_f32_e32 v144, v143
	s_waitcnt vmcnt(0)
	v_mul_f32_e32 v143, 0x3fb8aa3b, v145
	v_exp_f32_e32 v145, v143
	v_max_f32_e32 v146, 0, v142
	v_add_f32_e32 v147, 1.0, v144
	v_add_f32_e32 v148, -1.0, v147
	v_frexp_mant_f32_e32 v149, v147
	v_cvt_f64_f32_e32 v[142:143], v147
	v_sub_f32_e32 v150, v148, v147
	v_frexp_exp_i32_f64_e32 v142, v[142:143]
	v_cmp_gt_f32_e64 s[0:1], s82, v149
	v_sub_f32_e32 v148, v144, v148
	v_add_f32_e32 v143, 1.0, v150
	v_subbrev_co_u32_e64 v142, s[0:1], 0, v142, s[0:1]
	v_add_f32_e32 v143, v148, v143
	v_sub_u32_e32 v148, 0, v142
	v_cvt_f32_i32_e32 v142, v142
	v_ldexp_f32 v147, v147, v148
	v_ldexp_f32 v143, v143, v148
	v_add_f32_e32 v148, -1.0, v147
	v_add_f32_e32 v149, 1.0, v147
	v_add_f32_e32 v150, 1.0, v148
	v_add_f32_e32 v151, -1.0, v149
	v_sub_f32_e32 v150, v147, v150
	v_sub_f32_e32 v147, v147, v151
	v_mul_f32_e32 v151, 0x3f317218, v142
	v_add_f32_e32 v150, v143, v150
	v_add_f32_e32 v143, v143, v147
	v_fma_f32 v147, v142, s83, -v151
	v_add_f32_e32 v152, v148, v150
	v_add_f32_e32 v153, v149, v143
	v_fmac_f32_e32 v147, 0xb102e308, v142
	v_sub_f32_e32 v142, v152, v148
	v_sub_f32_e32 v148, v153, v149
	v_rcp_f32_e32 v149, v153
	v_add_f32_e32 v154, v151, v147
	v_sub_f32_e32 v143, v143, v148
	v_sub_f32_e32 v148, v154, v151
	v_sub_f32_e32 v147, v147, v148
	v_mul_f32_e32 v148, v152, v149
	v_sub_f32_e32 v142, v150, v142
	v_mul_f32_e32 v150, v153, v148
	v_fma_f32 v151, v148, v153, -v150
	v_fmac_f32_e32 v151, v148, v143
	v_add_f32_e32 v155, v150, v151
	v_sub_f32_e32 v171, v152, v155
	v_sub_f32_e32 v150, v155, v150
	v_sub_f32_e32 v152, v152, v171
	v_sub_f32_e32 v150, v150, v151
	v_sub_f32_e32 v151, v152, v155
	v_add_f32_e32 v142, v142, v151
	v_add_f32_e32 v142, v150, v142
	v_add_f32_e32 v150, v171, v142
	v_mul_f32_e32 v151, v149, v150
	v_sub_f32_e32 v152, v171, v150
	v_mul_f32_e32 v155, v153, v151
	v_add_f32_e32 v142, v142, v152
	v_add_f32_e32 v152, v148, v151
	v_fma_f32 v153, v151, v153, -v155
	v_sub_f32_e32 v148, v152, v148
	v_fmac_f32_e32 v153, v151, v143
	v_sub_f32_e32 v143, v151, v148
	v_add_f32_e32 v148, v155, v153
	v_sub_f32_e32 v151, v148, v155
	v_sub_f32_e32 v155, v150, v148
	v_sub_f32_e32 v150, v150, v155
	v_sub_f32_e32 v148, v150, v148
	v_sub_f32_e32 v151, v151, v153
	v_add_f32_e32 v142, v142, v148
	v_add_f32_e32 v142, v151, v142
	v_add_f32_e32 v142, v155, v142
	v_mul_f32_e32 v142, v149, v142
	v_add_f32_e32 v142, v143, v142
	v_add_f32_e32 v143, v152, v142
	v_mul_f32_e32 v148, v143, v143
	v_fmamk_f32 v151, v148, 0x3e9b6dac, v204
	v_sub_f32_e32 v149, v143, v152
	v_ldexp_f32 v150, v143, 1
	v_mul_f32_e32 v143, v143, v148
	v_fmaak_f32 v148, v148, v151, 0x3f2aaada
	v_mul_f32_e32 v143, v143, v148
	v_add_f32_e32 v148, v150, v143
	v_sub_f32_e32 v142, v142, v149
	v_sub_f32_e32 v149, v148, v150
	v_ldexp_f32 v142, v142, 1
	v_sub_f32_e32 v143, v143, v149
	v_add_f32_e32 v142, v142, v143
	v_add_f32_e32 v143, v148, v142
	v_sub_f32_e32 v148, v143, v148
	v_add_f32_e32 v149, v154, v143
	v_sub_f32_e32 v142, v142, v148
	v_sub_f32_e32 v148, v149, v154
	v_sub_f32_e32 v150, v149, v148
	v_sub_f32_e32 v143, v143, v148
	v_add_f32_e32 v148, v147, v142
	v_sub_f32_e32 v150, v154, v150
	v_sub_f32_e32 v151, v148, v147
	v_add_f32_e32 v143, v143, v150
	v_sub_f32_e32 v150, v148, v151
	v_sub_f32_e32 v142, v142, v151
	v_sub_f32_e32 v147, v147, v150
	v_add_f32_e32 v143, v148, v143
	v_add_f32_e32 v142, v142, v147
	v_add_f32_e32 v147, v149, v143
	v_sub_f32_e32 v148, v147, v149
	v_sub_f32_e32 v143, v143, v148
	v_add_f32_e32 v142, v142, v143
	v_add_f32_e32 v142, v147, v142
	v_cmp_neq_f32_e64 s[0:1], s84, v144
	s_nop 1
	v_cndmask_b32_e64 v142, v206, v142, s[0:1]
	v_cmp_ngt_f32_e64 s[0:1], -1.0, v144
	s_nop 1
	v_cndmask_b32_e64 v142, v207, v142, s[0:1]
	v_cmp_neq_f32_e64 s[0:1], -1.0, v144
	s_nop 1
	v_cndmask_b32_e64 v142, v208, v142, s[0:1]
	v_cmp_lt_f32_e64 s[0:1], |v144|, s85
	s_nop 1
	v_cndmask_b32_e64 v142, v142, v144, s[0:1]
	v_add_f32_e32 v142, v146, v142
	v_mul_f32_e64 v142, v142, -v145
	global_store_dword v[140:141], v142, off offset:12
